# carried-state row copies moved from phase 0 (latency-bound loops) to the idle tail of phase 1; PLE GEMM moved into the idle tail of phase 7
# speedup vs baseline: 1.0460x; 1.0149x over previous
; __device__ __forceinline__ void phase0(const Params& p, LAS unsigned char* lds, int wave_s) {
;     ...
;     { const int n4 = MS * 14 * 256;
;       for (int i = blockIdx.x * 512 + tid; i < n4; i += gridDim.x * 512) { const int s = i / (14 * 256), q = i % (14 * 256);
;           ((f32x4*)(p.out + O_POOLS + (size_t)s * 15 * 1024))[q] = ((const f32x4*)(p.in[4] + (size_t)s * 15 * 1024 + 1024))[q]; }
.LBB0_63:
	s_or_b64 exec, exec, s[6:7]
	s_mov_b32 s3, 0
	v_cmp_gt_i32_e32 vcc, s3, v17
	s_and_saveexec_b64 s[4:5], vcc
	s_cbranch_execz .LBB0_66
	s_lshl_b32 s3, s33, 9
	s_add_u32 s6, s20, 0x4584000
	s_addc_u32 s7, s21, 0
	s_mov_b64 s[8:9], 0
	s_mov_b32 s10, 0x92492493
	s_mov_b32 s11, 0x6ffff
	v_mov_b32_e32 v0, v17

; __device__ __forceinline__ void phase0(const Params& p, LAS unsigned char* lds, int wave_s) {
;     ...
;       const int m4 = MS * 2 * 1536;
;       for (int i = blockIdx.x * 512 + tid; i < m4; i += gridDim.x * 512) { const int s = i / (2 * 1536), q = i % (2 * 1536);
;           ((f32x4*)(p.out + O_CONVS + (size_t)s * 3 * 6144))[q] = ((const f32x4*)(p.in[5] + (size_t)s * 3 * 6144 + 6144))[q]; } }
.LBB0_66:
	s_or_b64 exec, exec, s[4:5]
	s_mov_b32 s3, 0
	v_cmp_gt_i32_e32 vcc, s3, v17
	s_and_saveexec_b64 s[4:5], vcc
	s_cbranch_execz .LBB0_69
	s_lshl_b32 s3, s33, 9
	s_add_u32 s10, s20, 0x4d04000
	s_addc_u32 s11, s21, 0
	s_mov_b64 s[6:7], 0
	s_mov_b32 s8, 0x2aaaaaab
	s_movk_i32 s9, 0x6000
	v_mov_b64_e32 v[0:1], s[62:63]
	v_mov_b64_e32 v[2:3], s[10:11]
	s_mov_b32 s10, 0x5ffff

; __device__ __forceinline__ void phase0(const Params& p, LAS unsigned char* lds, int wave_s) {
;     ...
;     { const int n4 = MS * 14 * 256;
;       for (int i = blockIdx.x * 512 + tid; i < n4; i += gridDim.x * 512) { const int s = i / (14 * 256), q = i % (14 * 256);
;           ((f32x4*)(p.out + O_POOLS + (size_t)s * 15 * 1024))[q] = ((const f32x4*)(p.in[4] + (size_t)s * 15 * 1024 + 1024))[q]; }
;       const int m4 = MS * 2 * 1536;
;       for (int i = blockIdx.x * 512 + tid; i < m4; i += gridDim.x * 512) { const int s = i / (2 * 1536), q = i % (2 * 1536);
;           ((f32x4*)(p.out + O_CONVS + (size_t)s * 3 * 6144))[q] = ((const f32x4*)(p.in[5] + (size_t)s * 3 * 6144 + 6144))[q]; } }
.LBB0_609:
	s_waitcnt vmcnt(0)
	s_barrier
	s_cmpk_lt_i32 s2, 0xd5
	s_cbranch_scc1 .Lscopy_skip
	s_mov_b64 exec, -1
	v_mbcnt_lo_u32_b32 v0, -1, 0
	v_mbcnt_hi_u32_b32 v0, -1, v0
	v_lshlrev_b32_e32 v1, 4, v0
	s_lshr_b32 s84, s24, 6
	s_sub_i32 s85, s2, 0xd5
	s_lshl_b32 s85, s85, 3
	s_add_i32 s85, s85, s84
	s_mov_b32 s86, s85
	s_add_u32 s92, s20, 0x4584000
	s_addc_u32 s93, s21, 0
.Lscopy_pool_loop:
	s_cmp_lt_u32 s86, 0x1c00
	s_cbranch_scc0 .Lscopy_pool_done
	s_add_i32 s87, s86, 0x0
	s_cmp_lt_u32 s87, 0x1c00
	s_cbranch_scc0 .Lscopy_pool_ld0
	s_mul_hi_u32 s88, s87, 0x4924925
	s_mul_i32 s89, s88, 0x38
	s_sub_i32 s89, s87, s89
	s_mul_i32 s88, s88, 0xf000
	s_lshl_b32 s89, s89, 10
	s_add_i32 s88, s88, s89
	s_add_i32 s88, s88, 0x1000
	v_add_u32_e32 v2, s88, v1
	global_load_dwordx4 v[8:11], v2, s[60:61]
.Lscopy_pool_ld0:
	s_add_i32 s87, s86, 0x158
	s_cmp_lt_u32 s87, 0x1c00
	s_cbranch_scc0 .Lscopy_pool_ld1
	s_mul_hi_u32 s88, s87, 0x4924925
	s_mul_i32 s89, s88, 0x38
	s_sub_i32 s89, s87, s89
	s_mul_i32 s88, s88, 0xf000
	s_lshl_b32 s89, s89, 10
	s_add_i32 s88, s88, s89
	s_add_i32 s88, s88, 0x1000
	v_add_u32_e32 v3, s88, v1
	global_load_dwordx4 v[12:15], v3, s[60:61]
.Lscopy_pool_ld1:
	s_add_i32 s87, s86, 0x2b0
	s_cmp_lt_u32 s87, 0x1c00
	s_cbranch_scc0 .Lscopy_pool_ld2
	s_mul_hi_u32 s88, s87, 0x4924925
	s_mul_i32 s89, s88, 0x38
	s_sub_i32 s89, s87, s89
	s_mul_i32 s88, s88, 0xf000
	s_lshl_b32 s89, s89, 10
	s_add_i32 s88, s88, s89
	s_add_i32 s88, s88, 0x1000
	v_add_u32_e32 v4, s88, v1
	global_load_dwordx4 v[16:19], v4, s[60:61]
.Lscopy_pool_ld2:
	s_add_i32 s87, s86, 0x408
	s_cmp_lt_u32 s87, 0x1c00
	s_cbranch_scc0 .Lscopy_pool_ld3
	s_mul_hi_u32 s88, s87, 0x4924925
	s_mul_i32 s89, s88, 0x38
	s_sub_i32 s89, s87, s89
	s_mul_i32 s88, s88, 0xf000
	s_lshl_b32 s89, s89, 10
	s_add_i32 s88, s88, s89
	s_add_i32 s88, s88, 0x1000
	v_add_u32_e32 v5, s88, v1
	global_load_dwordx4 v[20:23], v5, s[60:61]
.Lscopy_pool_ld3:
	s_waitcnt vmcnt(0)
	s_add_i32 s87, s86, 0x0
	s_cmp_lt_u32 s87, 0x1c00
	s_cbranch_scc0 .Lscopy_pool_st0
	v_add_u32_e32 v2, 0xfffff000, v2
	global_store_dwordx4 v2, v[8:11], s[92:93]
.Lscopy_pool_st0:
	s_add_i32 s87, s86, 0x158
	s_cmp_lt_u32 s87, 0x1c00
	s_cbranch_scc0 .Lscopy_pool_st1
	v_add_u32_e32 v3, 0xfffff000, v3
	global_store_dwordx4 v3, v[12:15], s[92:93]
.Lscopy_pool_st1:
	s_add_i32 s87, s86, 0x2b0
	s_cmp_lt_u32 s87, 0x1c00
	s_cbranch_scc0 .Lscopy_pool_st2
	v_add_u32_e32 v4, 0xfffff000, v4
	global_store_dwordx4 v4, v[16:19], s[92:93]
.Lscopy_pool_st2:
	s_add_i32 s87, s86, 0x408
	s_cmp_lt_u32 s87, 0x1c00
	s_cbranch_scc0 .Lscopy_pool_st3
	v_add_u32_e32 v5, 0xfffff000, v5
	global_store_dwordx4 v5, v[20:23], s[92:93]
.Lscopy_pool_st3:
	s_add_i32 s86, s86, 0x560
	s_branch .Lscopy_pool_loop
.Lscopy_pool_done:
	s_mov_b32 s86, s85
	s_add_u32 s92, s20, 0x4d04000
	s_addc_u32 s93, s21, 0
.Lscopy_conv_loop:
	s_cmp_lt_u32 s86, 0x1800
	s_cbranch_scc0 .Lscopy_conv_done
	s_add_i32 s87, s86, 0x0
	s_cmp_lt_u32 s87, 0x1800
	s_cbranch_scc0 .Lscopy_conv_ld0
	s_mul_hi_u32 s88, s87, 0x5555556
	s_mul_i32 s89, s88, 0x30
	s_sub_i32 s89, s87, s89
	s_mul_i32 s88, s88, 0x12000
	s_lshl_b32 s89, s89, 10
	s_add_i32 s88, s88, s89
	s_add_i32 s88, s88, 0x6000
	v_add_u32_e32 v2, s88, v1
	global_load_dwordx4 v[8:11], v2, s[62:63]
.Lscopy_conv_ld0:
	s_add_i32 s87, s86, 0x158
	s_cmp_lt_u32 s87, 0x1800
	s_cbranch_scc0 .Lscopy_conv_ld1
	s_mul_hi_u32 s88, s87, 0x5555556
	s_mul_i32 s89, s88, 0x30
	s_sub_i32 s89, s87, s89
	s_mul_i32 s88, s88, 0x12000
	s_lshl_b32 s89, s89, 10
	s_add_i32 s88, s88, s89
	s_add_i32 s88, s88, 0x6000
	v_add_u32_e32 v3, s88, v1
	global_load_dwordx4 v[12:15], v3, s[62:63]
.Lscopy_conv_ld1:
	s_add_i32 s87, s86, 0x2b0
	s_cmp_lt_u32 s87, 0x1800
	s_cbranch_scc0 .Lscopy_conv_ld2
	s_mul_hi_u32 s88, s87, 0x5555556
	s_mul_i32 s89, s88, 0x30
	s_sub_i32 s89, s87, s89
	s_mul_i32 s88, s88, 0x12000
	s_lshl_b32 s89, s89, 10
	s_add_i32 s88, s88, s89
	s_add_i32 s88, s88, 0x6000
	v_add_u32_e32 v4, s88, v1
	global_load_dwordx4 v[16:19], v4, s[62:63]
.Lscopy_conv_ld2:
	s_add_i32 s87, s86, 0x408
	s_cmp_lt_u32 s87, 0x1800
	s_cbranch_scc0 .Lscopy_conv_ld3
	s_mul_hi_u32 s88, s87, 0x5555556
	s_mul_i32 s89, s88, 0x30
	s_sub_i32 s89, s87, s89
	s_mul_i32 s88, s88, 0x12000
	s_lshl_b32 s89, s89, 10
	s_add_i32 s88, s88, s89
	s_add_i32 s88, s88, 0x6000
	v_add_u32_e32 v5, s88, v1
	global_load_dwordx4 v[20:23], v5, s[62:63]
.Lscopy_conv_ld3:
	s_waitcnt vmcnt(0)
	s_add_i32 s87, s86, 0x0
	s_cmp_lt_u32 s87, 0x1800
	s_cbranch_scc0 .Lscopy_conv_st0
	v_add_u32_e32 v2, 0xffffa000, v2
	global_store_dwordx4 v2, v[8:11], s[92:93]
.Lscopy_conv_st0:
	s_add_i32 s87, s86, 0x158
	s_cmp_lt_u32 s87, 0x1800
	s_cbranch_scc0 .Lscopy_conv_st1
	v_add_u32_e32 v3, 0xffffa000, v3
	global_store_dwordx4 v3, v[12:15], s[92:93]
.Lscopy_conv_st1:
	s_add_i32 s87, s86, 0x2b0
	s_cmp_lt_u32 s87, 0x1800
	s_cbranch_scc0 .Lscopy_conv_st2
	v_add_u32_e32 v4, 0xffffa000, v4
	global_store_dwordx4 v4, v[16:19], s[92:93]
.Lscopy_conv_st2:
	s_add_i32 s87, s86, 0x408
	s_cmp_lt_u32 s87, 0x1800
	s_cbranch_scc0 .Lscopy_conv_st3
	v_add_u32_e32 v5, 0xffffa000, v5
	global_store_dwordx4 v5, v[20:23], s[92:93]

; #define LAS __attribute__((address_space(3)))
; __device__ __forceinline__ unsigned xb_ld(unsigned* p)              { return __hip_atomic_load(p, __ATOMIC_RELAXED, __HIP_MEMORY_SCOPE_AGENT); }
; __device__ __forceinline__ unsigned xb_add(unsigned* p, unsigned v) { return __hip_atomic_fetch_add(p, v, __ATOMIC_RELAXED, __HIP_MEMORY_SCOPE_AGENT); }
; __device__ __forceinline__ unsigned xb_xcc_id() { return (unsigned)__builtin_amdgcn_s_getreg((3 << 11) | 20) & 0xFu; }
; __device__ __forceinline__ void xcd_barrier(unsigned* bar, volatile LAS unsigned* st, int wave_s) {
;     asm volatile("s_waitcnt vmcnt(0)" ::: "memory");
;     __syncthreads();
;     if (opaque_tid(wave_s) == 0) {
;         __builtin_amdgcn_s_waitcnt(0);
;         const unsigned x = xb_xcc_id();
;         unsigned nloc = st[0], nx = st[1];
;         if (nloc == 0u) {
;             const unsigned G = gridDim.x; unsigned sum, cnt, mine;
;             for (;;) { sum = 0u; cnt = 0u; mine = 0u;
; #pragma unroll
;                 for (unsigned j = 0; j < 16; ++j) { const unsigned c = xb_ld(&bar[XB_XCNT(j)]); sum += c; cnt += (c > 0u) ? 1u : 0u; mine = (j == x) ? c : mine; }
;                 if (sum == G) break;
;                 __builtin_amdgcn_s_sleep(1); }
;             nloc = mine > 0u ? mine : 1u; nx = cnt > 0u ? cnt : 1u; st[0] = nloc; st[1] = nx; }
;         const unsigned old = xb_add(&bar[XB_XSUB(x)], 1u);
;         const unsigned gen = old / nloc;
;         if (old + 1u == (gen + 1u) * nloc) {
;             __builtin_amdgcn_fence(__ATOMIC_RELEASE, "agent");
;             asm volatile("s_waitcnt vmcnt(0)" ::: "memory");
;             const unsigned og = xb_add(&bar[XB_TOP], 1u);
;             const unsigned tg = og / nx;
;             if (og + 1u == (tg + 1u) * nx) xb_add(&bar[XB_TOPGEN], 1u);
;             else { while (xb_ld(&bar[XB_TOPGEN]) == tg) __builtin_amdgcn_s_sleep(1); }
;             __builtin_amdgcn_fence(__ATOMIC_ACQUIRE, "agent");
;             xb_add(&bar[XB_XGEN(x)], 1u);
;             asm volatile("s_waitcnt vmcnt(0)" ::: "memory");
;         } else {
;             while (xb_ld(&bar[XB_XGEN(x)]) == gen) __builtin_amdgcn_s_sleep(1);
;             __builtin_amdgcn_fence(__ATOMIC_ACQUIRE, "agent");
;             asm volatile("s_waitcnt vmcnt(0)" ::: "memory");
;         }
;     }
;     __syncthreads();
.Lscopy_conv_done:
.Lscopy_skip:
.LBB0_610:
	s_cmp_gt_i32 s19, 2
	s_cselect_b64 s[0:1], -1, 0
	s_and_b64 s[4:5], s[10:11], s[0:1]
	s_andn2_b64 vcc, exec, s[4:5]
	s_cbranch_vccnz .LBB0_641
	s_waitcnt vmcnt(0)
	s_waitcnt vmcnt(0)
	s_barrier
	s_mov_b32 s3, 0
	s_nop 0
	v_mbcnt_lo_u32_b32 v0, -1, s3
	v_mbcnt_hi_u32_b32 v0, -1, v0
	v_or_b32_e32 v0, s24, v0
	s_nop 0
	v_cmp_eq_u32_e32 vcc, 0, v0
	s_and_saveexec_b64 s[4:5], vcc
	s_cbranch_execz .LBB0_640
	s_add_i32 s6, 0, 0x23ff0
	v_mov_b32_e32 v0, s6
	s_waitcnt vmcnt(0) expcnt(0) lgkmcnt(0)
	s_getreg_b32 s3, hwreg(HW_REG_XCC_ID, 0, 4)
	ds_read_b32 v1, v0
	s_add_i32 s6, 0, 0x23ff4
	v_mov_b32_e32 v0, s6
	ds_read_b32 v0, v0
	s_and_b32 s3, s3, 15
	s_waitcnt lgkmcnt(1)
	v_cmp_ne_u32_e32 vcc, 0, v1
	s_cbranch_vccnz .LBB0_618
	s_add_u32 s6, s22, 0x1f32a400
	s_addc_u32 s7, s23, 0
	s_add_u32 s8, s22, 0x1f32a500
	s_addc_u32 s9, s23, 0
	s_add_u32 s10, s22, 0x1f32a600
	s_addc_u32 s11, s23, 0
	s_add_u32 s12, s22, 0x1f32a700
	s_addc_u32 s13, s23, 0
	s_add_u32 s14, s22, 0x1f32a800
	s_addc_u32 s15, s23, 0
	s_add_u32 s16, s22, 0x1f32a900
	s_addc_u32 s17, s23, 0
	s_add_u32 s26, s22, 0x1f32aa00
	s_addc_u32 s27, s23, 0
	s_add_u32 s28, s22, 0x1f32ab00
	s_addc_u32 s29, s23, 0
	s_add_u32 s30, s22, 0x1f32ac00
	s_addc_u32 s31, s23, 0
	s_add_u32 s34, s22, 0x1f32ad00
	s_addc_u32 s35, s23, 0
	s_add_u32 s36, s22, 0x1f32ae00
	s_addc_u32 s37, s23, 0
	s_add_u32 s38, s22, 0x1f32af00
	s_addc_u32 s39, s23, 0
	s_add_u32 s40, s22, 0x1f32b000
	s_addc_u32 s41, s23, 0
	s_add_u32 s42, s22, 0x1f32b100
	s_addc_u32 s43, s23, 0
	s_add_u32 s44, s22, 0x1f32b200
	s_addc_u32 s45, s23, 0
	s_add_u32 s46, s22, 0x1f32b300
	s_addc_u32 s47, s23, 0
	v_mov_b32_e32 v16, 0
	s_branch .LBB0_615

;     __device__ bool next(int i, Unit& u) const {
;         const long L = (long)i * G + c; if (L >= nwg) return false;
;         int wgid = (int)L; { const int q = nwg / NXCD, r = nwg % NXCD, xcd = wgid % NXCD, off = wgid / NXCD; wgid = (xcd < r ? xcd * (q + 1) : r * (q + 1) + (xcd - r) * q) + off; }
;         const int nig = WGM * nN, gid = wgid / nig, fm = gid * WGM, gsz = (nM - fm) < WGM ? (nM - fm) : WGM;
;         u.pm = fm + ((wgid % nig) % gsz); u.pn = (wgid % nig) / gsz; return true;
; __global__ void __launch_bounds__(512, 2) mega(Params p) {
;     ...
;         { pg8::Gemm g{(const bf16_t*)(ws + WS_PBF), (const bf16_t*)(ws + WS_WPLE), 256, 256, 256, 32, 8, 0};
;           pg8::StaticOrder S; S.init(32, 8, G, bx);
;           EpiPle E{(bf16_t*)(ws + WS_T2)};
;           pg8::gemm_phase(lds, g, S, E, wave_s); }
.LBB0_1234:
	s_waitcnt vmcnt(0)
	s_barrier
	s_cmpk_lt_i32 s2, 0xac
	s_cbranch_scc1 .Lp9a_skip
	v_writelane_b32 v254, s2, 36
	v_writelane_b32 v254, s33, 37
	s_sub_i32 s2, s2, 0xac
	s_movk_i32 s33, 0x54
	s_add_u32 s6, s22, 0x5f80000
	s_addc_u32 s7, s23, 0
	s_add_u32 s8, s22, 0x5680000
	s_addc_u32 s9, s23, 0
	s_add_u32 s10, s22, 0x13b2a000
	s_mov_b32 s0, 0
	s_addc_u32 s11, s23, 0
	v_mbcnt_lo_u32_b32 v0, -1, s0
	v_mbcnt_hi_u32_b32 v0, -1, v0
	v_or_b32_e32 v8, s24, v0
	s_cmpk_lt_i32 s2, 0x100
	s_cselect_b64 s[26:27], -1, 0
	s_cmpk_gt_i32 s2, 0xff
	v_readfirstlane_b32 s16, v8
	s_cbranch_scc1 .Lp9a_1354
	s_ashr_i32 s29, s2, 31
	s_lshr_b32 s0, s29, 29
	s_add_i32 s3, s2, s0
	s_and_b32 s0, s3, -8
	s_sub_i32 s13, s2, s0
	s_cmp_gt_i32 s13, -1
	s_cbranch_scc0 .Lp9a_1335
	s_lshl_b32 s12, s13, 5
	s_cbranch_execz .Lp9a_1336
	s_branch .Lp9a_1337

; #define LAS __attribute__((address_space(3)))
; __device__ __forceinline__ unsigned xb_ld(unsigned* p)              { return __hip_atomic_load(p, __ATOMIC_RELAXED, __HIP_MEMORY_SCOPE_AGENT); }
; __device__ __forceinline__ unsigned xb_add(unsigned* p, unsigned v) { return __hip_atomic_fetch_add(p, v, __ATOMIC_RELAXED, __HIP_MEMORY_SCOPE_AGENT); }
; __device__ __forceinline__ unsigned xb_xcc_id() { return (unsigned)__builtin_amdgcn_s_getreg((3 << 11) | 20) & 0xFu; }
; __device__ __forceinline__ void xcd_barrier(unsigned* bar, volatile LAS unsigned* st, int wave_s) {
;     asm volatile("s_waitcnt vmcnt(0)" ::: "memory");
;     __syncthreads();
;     if (opaque_tid(wave_s) == 0) {
;         __builtin_amdgcn_s_waitcnt(0);
;         const unsigned x = xb_xcc_id();
;         unsigned nloc = st[0], nx = st[1];
;         if (nloc == 0u) {
;             const unsigned G = gridDim.x; unsigned sum, cnt, mine;
;             for (;;) { sum = 0u; cnt = 0u; mine = 0u;
; #pragma unroll
;                 for (unsigned j = 0; j < 16; ++j) { const unsigned c = xb_ld(&bar[XB_XCNT(j)]); sum += c; cnt += (c > 0u) ? 1u : 0u; mine = (j == x) ? c : mine; }
;                 if (sum == G) break;
;                 __builtin_amdgcn_s_sleep(1); }
;             nloc = mine > 0u ? mine : 1u; nx = cnt > 0u ? cnt : 1u; st[0] = nloc; st[1] = nx; }
;         const unsigned old = xb_add(&bar[XB_XSUB(x)], 1u);
;         const unsigned gen = old / nloc;
;         if (old + 1u == (gen + 1u) * nloc) {
;             __builtin_amdgcn_fence(__ATOMIC_RELEASE, "agent");
;             asm volatile("s_waitcnt vmcnt(0)" ::: "memory");
;             const unsigned og = xb_add(&bar[XB_TOP], 1u);
;             const unsigned tg = og / nx;
;             if (og + 1u == (tg + 1u) * nx) xb_add(&bar[XB_TOPGEN], 1u);
;             else { while (xb_ld(&bar[XB_TOPGEN]) == tg) __builtin_amdgcn_s_sleep(1); }
;             __builtin_amdgcn_fence(__ATOMIC_ACQUIRE, "agent");
;             xb_add(&bar[XB_XGEN(x)], 1u);
;             asm volatile("s_waitcnt vmcnt(0)" ::: "memory");
;         } else {
;             while (xb_ld(&bar[XB_XGEN(x)]) == gen) __builtin_amdgcn_s_sleep(1);
;             __builtin_amdgcn_fence(__ATOMIC_ACQUIRE, "agent");
;             asm volatile("s_waitcnt vmcnt(0)" ::: "memory");
;         }
;     }
;     __syncthreads();
.Lp9a_1354:
	v_readlane_b32 s2, v254, 36
	v_readlane_b32 s33, v254, 37
	s_nop 4
.Lp9a_skip:
.LBB0_1235:
	s_cmp_gt_i32 s19, 8
	s_cselect_b64 s[0:1], -1, 0
	s_and_b64 s[4:5], s[4:5], s[0:1]
	s_andn2_b64 vcc, exec, s[4:5]
	s_cbranch_vccnz .LBB0_1266
	s_waitcnt vmcnt(0)
	s_waitcnt vmcnt(0)
	s_barrier
	s_mov_b32 s3, 0
	s_nop 0
	v_mbcnt_lo_u32_b32 v0, -1, s3
	v_mbcnt_hi_u32_b32 v0, -1, v0
	v_or_b32_e32 v0, s24, v0
	s_nop 0
	v_cmp_eq_u32_e32 vcc, 0, v0
	s_and_saveexec_b64 s[4:5], vcc
	s_cbranch_execz .LBB0_1265
	s_add_i32 s6, 0, 0x23ff0
	v_mov_b32_e32 v0, s6
	s_waitcnt vmcnt(0) expcnt(0) lgkmcnt(0)
	s_getreg_b32 s3, hwreg(HW_REG_XCC_ID, 0, 4)
	ds_read_b32 v1, v0
	s_add_i32 s6, 0, 0x23ff4
	v_mov_b32_e32 v0, s6
	ds_read_b32 v0, v0
	s_and_b32 s3, s3, 15
	s_waitcnt lgkmcnt(1)
	v_cmp_ne_u32_e32 vcc, 0, v1
	s_cbranch_vccnz .LBB0_1243
	s_add_u32 s6, s22, 0x1f32a400
	s_addc_u32 s7, s23, 0
	s_add_u32 s8, s22, 0x1f32a500
	s_addc_u32 s9, s23, 0
	s_add_u32 s10, s22, 0x1f32a600
	s_addc_u32 s11, s23, 0
	s_add_u32 s12, s22, 0x1f32a700
	s_addc_u32 s13, s23, 0
	s_add_u32 s14, s22, 0x1f32a800
	s_addc_u32 s15, s23, 0
	s_add_u32 s16, s22, 0x1f32a900
	s_addc_u32 s17, s23, 0
	s_add_u32 s26, s22, 0x1f32aa00
	s_addc_u32 s27, s23, 0
	s_add_u32 s28, s22, 0x1f32ab00
	s_addc_u32 s29, s23, 0
	s_add_u32 s30, s22, 0x1f32ac00
	s_addc_u32 s31, s23, 0
	s_add_u32 s34, s22, 0x1f32ad00
	s_addc_u32 s35, s23, 0
	s_add_u32 s36, s22, 0x1f32ae00
	s_addc_u32 s37, s23, 0
	s_add_u32 s38, s22, 0x1f32af00
	s_addc_u32 s39, s23, 0
	s_add_u32 s40, s22, 0x1f32b000
	s_addc_u32 s41, s23, 0
	s_add_u32 s42, s22, 0x1f32b100
	s_addc_u32 s43, s23, 0
	s_add_u32 s44, s22, 0x1f32b200
	s_addc_u32 s45, s23, 0
	s_add_u32 s46, s22, 0x1f32b300
	s_addc_u32 s47, s23, 0
	v_mov_b32_e32 v16, 0
	s_branch .LBB0_1240

; __global__ void __launch_bounds__(512, 2) mega(Params p) {
;     ...
;     if (IN(9)) {
;         { pg8::Gemm g{(const bf16_t*)(ws + WS_PBF), (const bf16_t*)(ws + WS_WPLE), 256, 256, 256, 32, 8, 0};
;           pg8::StaticOrder S; S.init(32, 8, G, bx);
;           EpiPle E{(bf16_t*)(ws + WS_T2)};
;           pg8::gemm_phase(lds, g, S, E, wave_s); }
.LBB0_1331:
	s_cmp_lt_i32 s18, 10
	s_cselect_b64 s[4:5], -1, 0
	s_and_b64 s[4:5], s[4:5], s[0:1]
	s_andn2_b64 vcc, exec, s[4:5]
	s_cbranch_vccnz .LBB0_1381
	s_add_u32 s6, s22, 0x5f80000
	s_addc_u32 s7, s23, 0
	s_add_u32 s8, s22, 0x5680000
	s_addc_u32 s9, s23, 0
	s_add_u32 s10, s22, 0x13b2a000
	s_mov_b32 s0, 0
	s_addc_u32 s11, s23, 0
	v_mbcnt_lo_u32_b32 v0, -1, s0
	v_mbcnt_hi_u32_b32 v0, -1, v0
	v_or_b32_e32 v8, s24, v0
	s_cmpk_lt_i32 s2, 0x100
	s_cselect_b64 s[26:27], -1, 0
	s_cmpk_gt_i32 s2, 0xff
	v_readfirstlane_b32 s16, v8
	s_branch .LBB0_1354
